# ph7 epilogue: residual loads software-prefetched 3 rows deep into dead fragment regs (saddr form), arithmetic unchanged
# speedup vs baseline: 1.0410x; 1.0055x over previous
.LBB0_895:
	v_lshl_add_u32 v146, s38, 8, v148
	v_lshl_or_b32 v144, s6, 8, v150
	v_ashrrev_i32_e32 v147, 31, v146
	v_ashrrev_i32_e32 v145, 31, v144
	v_lshlrev_b64 v[156:157], 10, v[146:147]
	v_lshl_add_u64 v[160:161], v[156:157], 0, v[144:145]
	v_lshlrev_b32_e32 v168, 2, v160
	s_add_u32 s98, s36, 0x0
	s_addc_u32 s99, s37, 0
	global_load_dwordx4 v[172:175], v168, s[98:99]
	global_load_dwordx4 v[176:179], v168, s[98:99] offset:16
	global_load_dwordx4 v[182:185], v168, s[98:99] offset:512
	global_load_dwordx4 v[186:189], v168, s[98:99] offset:528
	s_add_u32 s98, s36, 0x10000
	s_addc_u32 s99, s37, 0
	global_load_dwordx4 v[190:193], v168, s[98:99]
	global_load_dwordx4 v[194:197], v168, s[98:99] offset:16
	global_load_dwordx4 v[198:201], v168, s[98:99] offset:512
	global_load_dwordx4 v[202:205], v168, s[98:99] offset:528
	s_add_u32 s98, s36, 0x20000
	s_addc_u32 s99, s37, 0
	global_load_dwordx4 v[206:209], v168, s[98:99]
	global_load_dwordx4 v[212:215], v168, s[98:99] offset:16
	global_load_dwordx4 v[216:219], v168, s[98:99] offset:512
	global_load_dwordx4 v[220:223], v168, s[98:99] offset:528
	v_lshl_add_u64 v[160:161], v[160:161], 1, s[40:41]
	v_xor_b32_e32 v155, 32, v154
	s_lshl_b32 s38, s6, 2
	s_ashr_i32 s39, s38, 31
	s_waitcnt vmcnt(8)
	v_pk_add_f32 v[126:127], v[126:127], v[174:175]
	v_pk_add_f32 v[170:171], v[124:125], v[172:173]
	v_pk_add_f32 v[166:167], v[122:123], v[178:179]
	v_pk_add_f32 v[164:165], v[120:121], v[176:177]
	v_cvt_pk_bf16_f32 v120, v170, v171
	v_cvt_pk_bf16_f32 v121, v126, v127
	v_cvt_pk_bf16_f32 v122, v164, v165
	v_cvt_pk_bf16_f32 v123, v166, v167
	global_store_dwordx4 v[160:161], v[120:123], off
	s_nop 0
	s_nop 0
	v_and_b32_e32 v121, 64, v154
	v_xor_b32_e32 v120, 16, v154
	v_add_u32_e32 v121, 64, v121
	v_cmp_lt_i32_e32 vcc, v120, v121
	v_mul_f32_e32 v127, v127, v127
	v_mul_f32_e32 v163, v165, v165
	v_cndmask_b32_e32 v120, v154, v120, vcc
	v_cmp_lt_i32_e32 vcc, v155, v121
	v_mul_f32_e32 v165, v167, v167
	v_fmac_f32_e32 v127, v126, v126
	v_cndmask_b32_e32 v121, v154, v155, vcc
	v_mul_f32_e32 v155, v171, v171
	v_fmac_f32_e32 v155, v170, v170
	v_fmac_f32_e32 v163, v164, v164
	v_fmac_f32_e32 v165, v166, v166
	v_add_f32_e32 v126, v155, v127
	v_add_f32_e32 v127, v163, v165
	v_add_f32_e32 v126, v126, v127
	v_lshlrev_b32_e32 v120, 2, v120
	v_pk_add_f32 v[118:119], v[118:119], v[184:185]
	v_pk_add_f32 v[116:117], v[116:117], v[182:183]
	v_pk_add_f32 v[122:123], v[114:115], v[188:189]
	v_pk_add_f32 v[124:125], v[112:113], v[186:187]
	v_mul_f32_e32 v112, v117, v117
	v_mul_f32_e32 v113, v119, v119
	v_mul_f32_e32 v114, v125, v125
	v_mul_f32_e32 v115, v123, v123
	v_fmac_f32_e32 v112, v116, v116
	v_fmac_f32_e32 v113, v118, v118
	v_fmac_f32_e32 v114, v124, v124
	v_fmac_f32_e32 v115, v122, v122
	v_add_f32_e32 v112, v112, v113
	v_add_f32_e32 v113, v114, v115
	v_add_f32_e32 v112, v112, v113
	v_add_f32_e32 v112, v126, v112
	ds_bpermute_b32 v113, v120, v112
	v_lshlrev_b32_e32 v114, 2, v121
	v_cvt_pk_bf16_f32 v116, v116, v117
	v_cvt_pk_bf16_f32 v117, v118, v119
	v_cvt_pk_bf16_f32 v118, v124, v125
	s_waitcnt lgkmcnt(0)
	v_add_f32_e32 v112, v112, v113
	ds_bpermute_b32 v113, v114, v112
	v_cvt_pk_bf16_f32 v119, v122, v123
	global_store_dwordx4 v[160:161], v[116:119], off offset:256
	s_add_u32 s98, s36, 0x30000
	s_addc_u32 s99, s37, 0
	global_load_dwordx4 v[172:175], v168, s[98:99]
	global_load_dwordx4 v[176:179], v168, s[98:99] offset:16
	global_load_dwordx4 v[182:185], v168, s[98:99] offset:512
	global_load_dwordx4 v[186:189], v168, s[98:99] offset:528
	s_and_saveexec_b64 s[44:45], s[0:1]
	s_cbranch_execz .LBB0_897
	v_lshlrev_b64 v[116:117], 6, v[146:147]
	v_lshl_add_u64 v[116:117], s[16:17], 0, v[116:117]
	v_lshl_add_u64 v[116:117], s[38:39], 2, v[116:117]
	s_lshl_b32 s6, s54, 2
	v_lshl_add_u64 v[116:117], v[116:117], 0, s[6:7]
	s_waitcnt lgkmcnt(0)
	v_add_f32_e32 v112, v112, v113
	global_store_dword v[116:117], v112, off
.LBB0_897:
	s_or_b64 exec, exec, s[44:45]
	v_or_b32_e32 v112, 16, v146
	s_waitcnt lgkmcnt(0)
	v_ashrrev_i32_e32 v113, 31, v112
	v_lshlrev_b64 v[116:117], 10, v[112:113]
	v_lshl_add_u64 v[126:127], v[116:117], 0, v[144:145]
	v_lshl_add_u64 v[156:157], v[126:127], 2, s[36:37]
	v_lshl_add_u64 v[126:127], v[126:127], 1, s[40:41]
	s_waitcnt vmcnt(10)
	v_pk_add_f32 v[118:119], v[110:111], v[192:193]
	v_pk_add_f32 v[116:117], v[108:109], v[190:191]
	v_pk_add_f32 v[124:125], v[106:107], v[196:197]
	v_pk_add_f32 v[122:123], v[104:105], v[194:195]
	v_cvt_pk_bf16_f32 v104, v116, v117
	v_cvt_pk_bf16_f32 v105, v118, v119
	v_cvt_pk_bf16_f32 v106, v122, v123
	v_cvt_pk_bf16_f32 v107, v124, v125
	global_store_dwordx4 v[126:127], v[104:107], off
	s_nop 0
	v_mul_f32_e32 v115, v117, v117
	v_mul_f32_e32 v117, v119, v119
	v_mul_f32_e32 v119, v123, v123
	v_mul_f32_e32 v121, v125, v125
	v_fmac_f32_e32 v115, v116, v116
	v_fmac_f32_e32 v117, v118, v118
	v_fmac_f32_e32 v119, v122, v122
	v_fmac_f32_e32 v121, v124, v124
	v_add_f32_e32 v115, v115, v117
	v_add_f32_e32 v116, v119, v121
	v_add_f32_e32 v115, v115, v116
	v_pk_add_f32 v[102:103], v[102:103], v[200:201]
	v_pk_add_f32 v[100:101], v[100:101], v[198:199]
	v_pk_add_f32 v[104:105], v[98:99], v[204:205]
	v_pk_add_f32 v[106:107], v[96:97], v[202:203]
	v_mul_f32_e32 v96, v101, v101
	v_mul_f32_e32 v97, v103, v103
	v_mul_f32_e32 v98, v107, v107
	v_mul_f32_e32 v99, v105, v105
	v_fmac_f32_e32 v96, v100, v100
	v_fmac_f32_e32 v97, v102, v102
	v_fmac_f32_e32 v98, v106, v106
	v_fmac_f32_e32 v99, v104, v104
	v_add_f32_e32 v96, v96, v97
	v_add_f32_e32 v97, v98, v99
	v_add_f32_e32 v96, v96, v97
	v_add_f32_e32 v96, v115, v96
	ds_bpermute_b32 v97, v120, v96
	v_cvt_pk_bf16_f32 v98, v100, v101
	v_cvt_pk_bf16_f32 v99, v102, v103
	v_cvt_pk_bf16_f32 v100, v106, v107
	v_cvt_pk_bf16_f32 v101, v104, v105
	s_waitcnt lgkmcnt(0)
	v_add_f32_e32 v96, v96, v97
	ds_bpermute_b32 v97, v114, v96
	global_store_dwordx4 v[126:127], v[98:101], off offset:256
	s_add_u32 s98, s36, 0x80000
	s_addc_u32 s99, s37, 0
	global_load_dwordx4 v[190:193], v168, s[98:99]
	global_load_dwordx4 v[194:197], v168, s[98:99] offset:16
	global_load_dwordx4 v[198:201], v168, s[98:99] offset:512
	global_load_dwordx4 v[202:205], v168, s[98:99] offset:528
	s_and_saveexec_b64 s[44:45], s[0:1]
	s_cbranch_execz .LBB0_899
	v_lshlrev_b64 v[98:99], 6, v[112:113]
	v_lshl_add_u64 v[98:99], s[16:17], 0, v[98:99]
	v_lshl_add_u64 v[98:99], s[38:39], 2, v[98:99]
	s_lshl_b32 s6, s54, 2
	v_lshl_add_u64 v[98:99], v[98:99], 0, s[6:7]
	s_waitcnt lgkmcnt(0)
	v_add_f32_e32 v96, v96, v97
	global_store_dword v[98:99], v96, off
.LBB0_899:
	s_or_b64 exec, exec, s[44:45]
	v_or_b32_e32 v96, 32, v146
	s_waitcnt lgkmcnt(0)
	v_ashrrev_i32_e32 v97, 31, v96
	v_lshlrev_b64 v[98:99], 10, v[96:97]
	v_lshl_add_u64 v[106:107], v[98:99], 0, v[144:145]
	v_lshl_add_u64 v[108:109], v[106:107], 2, s[36:37]
	v_lshl_add_u64 v[106:107], v[106:107], 1, s[40:41]
	s_waitcnt vmcnt(12)
	v_pk_add_f32 v[100:101], v[94:95], v[208:209]
	v_pk_add_f32 v[98:99], v[92:93], v[206:207]
	v_pk_add_f32 v[104:105], v[90:91], v[214:215]
	v_pk_add_f32 v[102:103], v[88:89], v[212:213]
	v_cvt_pk_bf16_f32 v88, v98, v99
	v_cvt_pk_bf16_f32 v89, v100, v101
	v_cvt_pk_bf16_f32 v90, v102, v103
	v_cvt_pk_bf16_f32 v91, v104, v105
	global_store_dwordx4 v[106:107], v[88:91], off
	s_nop 0
	v_mul_f32_e32 v99, v99, v99
	v_mul_f32_e32 v101, v101, v101
	v_mul_f32_e32 v103, v103, v103
	v_mul_f32_e32 v105, v105, v105
	v_fmac_f32_e32 v99, v98, v98
	v_fmac_f32_e32 v101, v100, v100
	v_fmac_f32_e32 v103, v102, v102
	v_fmac_f32_e32 v105, v104, v104
	v_add_f32_e32 v98, v99, v101
	v_add_f32_e32 v99, v103, v105
	v_add_f32_e32 v98, v98, v99
	v_pk_add_f32 v[86:87], v[86:87], v[218:219]
	v_pk_add_f32 v[84:85], v[84:85], v[216:217]
	v_pk_add_f32 v[88:89], v[82:83], v[222:223]
	v_pk_add_f32 v[90:91], v[80:81], v[220:221]
	v_mul_f32_e32 v80, v85, v85
	v_mul_f32_e32 v81, v87, v87
	v_mul_f32_e32 v82, v91, v91
	v_mul_f32_e32 v83, v89, v89
	v_fmac_f32_e32 v80, v84, v84
	v_fmac_f32_e32 v81, v86, v86
	v_fmac_f32_e32 v82, v90, v90
	v_fmac_f32_e32 v83, v88, v88
	v_add_f32_e32 v80, v80, v81
	v_add_f32_e32 v81, v82, v83
	v_add_f32_e32 v80, v80, v81
	v_add_f32_e32 v80, v98, v80
	ds_bpermute_b32 v81, v120, v80
	v_cvt_pk_bf16_f32 v82, v84, v85
	v_cvt_pk_bf16_f32 v83, v86, v87
	v_cvt_pk_bf16_f32 v84, v90, v91
	v_cvt_pk_bf16_f32 v85, v88, v89
	s_waitcnt lgkmcnt(0)
	v_add_f32_e32 v80, v80, v81
	ds_bpermute_b32 v81, v114, v80
	global_store_dwordx4 v[106:107], v[82:85], off offset:256
	s_add_u32 s98, s36, 0x90000
	s_addc_u32 s99, s37, 0
	global_load_dwordx4 v[206:209], v168, s[98:99]
	global_load_dwordx4 v[212:215], v168, s[98:99] offset:16
	global_load_dwordx4 v[216:219], v168, s[98:99] offset:512
	global_load_dwordx4 v[220:223], v168, s[98:99] offset:528
	s_and_saveexec_b64 s[44:45], s[0:1]
	s_cbranch_execz .LBB0_901
	v_lshlrev_b64 v[82:83], 6, v[96:97]
	v_lshl_add_u64 v[82:83], s[16:17], 0, v[82:83]
	v_lshl_add_u64 v[82:83], s[38:39], 2, v[82:83]
	s_lshl_b32 s6, s54, 2
	v_lshl_add_u64 v[82:83], v[82:83], 0, s[6:7]
	s_waitcnt lgkmcnt(0)
	v_add_f32_e32 v80, v80, v81
	global_store_dword v[82:83], v80, off
.LBB0_901:
	s_or_b64 exec, exec, s[44:45]
	v_or_b32_e32 v80, 48, v146
	s_waitcnt lgkmcnt(0)
	v_ashrrev_i32_e32 v81, 31, v80
	v_lshlrev_b64 v[82:83], 10, v[80:81]
	v_lshl_add_u64 v[90:91], v[82:83], 0, v[144:145]
	v_lshl_add_u64 v[92:93], v[90:91], 2, s[36:37]
	v_lshl_add_u64 v[90:91], v[90:91], 1, s[40:41]
	s_waitcnt vmcnt(12)
	v_pk_add_f32 v[84:85], v[78:79], v[174:175]
	v_pk_add_f32 v[82:83], v[76:77], v[172:173]
	v_pk_add_f32 v[88:89], v[74:75], v[178:179]
	v_pk_add_f32 v[86:87], v[72:73], v[176:177]
	v_cvt_pk_bf16_f32 v72, v82, v83
	v_cvt_pk_bf16_f32 v73, v84, v85
	v_cvt_pk_bf16_f32 v74, v86, v87
	v_cvt_pk_bf16_f32 v75, v88, v89
	global_store_dwordx4 v[90:91], v[72:75], off
	s_nop 0
	v_mul_f32_e32 v83, v83, v83
	v_mul_f32_e32 v85, v85, v85
	v_mul_f32_e32 v87, v87, v87
	v_mul_f32_e32 v89, v89, v89
	v_fmac_f32_e32 v83, v82, v82
	v_fmac_f32_e32 v85, v84, v84
	v_fmac_f32_e32 v87, v86, v86
	v_fmac_f32_e32 v89, v88, v88
	v_add_f32_e32 v82, v83, v85
	v_add_f32_e32 v83, v87, v89
	v_add_f32_e32 v82, v82, v83
	v_pk_add_f32 v[70:71], v[70:71], v[184:185]
	v_pk_add_f32 v[68:69], v[68:69], v[182:183]
	v_pk_add_f32 v[72:73], v[66:67], v[188:189]
	v_pk_add_f32 v[74:75], v[64:65], v[186:187]
	v_mul_f32_e32 v64, v69, v69
	v_mul_f32_e32 v65, v71, v71
	v_mul_f32_e32 v66, v75, v75
	v_mul_f32_e32 v67, v73, v73
	v_fmac_f32_e32 v64, v68, v68
	v_fmac_f32_e32 v65, v70, v70
	v_fmac_f32_e32 v66, v74, v74
	v_fmac_f32_e32 v67, v72, v72
	v_add_f32_e32 v64, v64, v65
	v_add_f32_e32 v65, v66, v67
	v_add_f32_e32 v64, v64, v65
	v_add_f32_e32 v64, v82, v64
	ds_bpermute_b32 v65, v120, v64
	v_cvt_pk_bf16_f32 v66, v68, v69
	v_cvt_pk_bf16_f32 v67, v70, v71
	v_cvt_pk_bf16_f32 v68, v74, v75
	v_cvt_pk_bf16_f32 v69, v72, v73
	s_waitcnt lgkmcnt(0)
	v_add_f32_e32 v64, v64, v65
	ds_bpermute_b32 v65, v114, v64
	global_store_dwordx4 v[90:91], v[66:69], off offset:256
	s_add_u32 s98, s36, 0xa0000
	s_addc_u32 s99, s37, 0
	global_load_dwordx4 v[172:175], v168, s[98:99]
	global_load_dwordx4 v[176:179], v168, s[98:99] offset:16
	global_load_dwordx4 v[182:185], v168, s[98:99] offset:512
	global_load_dwordx4 v[186:189], v168, s[98:99] offset:528
	s_and_saveexec_b64 s[44:45], s[0:1]
	s_cbranch_execz .LBB0_903
	v_lshlrev_b64 v[66:67], 6, v[80:81]
	v_lshl_add_u64 v[66:67], s[16:17], 0, v[66:67]
	v_lshl_add_u64 v[66:67], s[38:39], 2, v[66:67]
	s_lshl_b32 s6, s54, 2
	v_lshl_add_u64 v[66:67], v[66:67], 0, s[6:7]
	s_waitcnt lgkmcnt(0)
	v_add_f32_e32 v64, v64, v65
	global_store_dword v[66:67], v64, off
.LBB0_903:
	s_or_b64 exec, exec, s[44:45]
	v_add_u32_e32 v64, 0x80, v146
	s_waitcnt lgkmcnt(0)
	v_ashrrev_i32_e32 v65, 31, v64
	v_lshlrev_b64 v[66:67], 10, v[64:65]
	v_lshl_add_u64 v[74:75], v[66:67], 0, v[144:145]
	v_lshl_add_u64 v[76:77], v[74:75], 2, s[36:37]
	v_lshl_add_u64 v[74:75], v[74:75], 1, s[40:41]
	s_waitcnt vmcnt(12)
	v_pk_add_f32 v[68:69], v[62:63], v[192:193]
	v_pk_add_f32 v[66:67], v[60:61], v[190:191]
	v_pk_add_f32 v[72:73], v[58:59], v[196:197]
	v_pk_add_f32 v[70:71], v[56:57], v[194:195]
	v_cvt_pk_bf16_f32 v56, v66, v67
	v_cvt_pk_bf16_f32 v57, v68, v69
	v_cvt_pk_bf16_f32 v58, v70, v71
	v_cvt_pk_bf16_f32 v59, v72, v73
	global_store_dwordx4 v[74:75], v[56:59], off
	s_nop 0
	v_mul_f32_e32 v67, v67, v67
	v_mul_f32_e32 v69, v69, v69
	v_mul_f32_e32 v71, v71, v71
	v_mul_f32_e32 v73, v73, v73
	v_fmac_f32_e32 v67, v66, v66
	v_fmac_f32_e32 v69, v68, v68
	v_fmac_f32_e32 v71, v70, v70
	v_fmac_f32_e32 v73, v72, v72
	v_add_f32_e32 v66, v67, v69
	v_add_f32_e32 v67, v71, v73
	v_add_f32_e32 v66, v66, v67
	v_pk_add_f32 v[54:55], v[54:55], v[200:201]
	v_pk_add_f32 v[52:53], v[52:53], v[198:199]
	v_pk_add_f32 v[56:57], v[50:51], v[204:205]
	v_pk_add_f32 v[58:59], v[48:49], v[202:203]
	v_mul_f32_e32 v48, v53, v53
	v_mul_f32_e32 v49, v55, v55
	v_mul_f32_e32 v50, v59, v59
	v_mul_f32_e32 v51, v57, v57
	v_fmac_f32_e32 v48, v52, v52
	v_fmac_f32_e32 v49, v54, v54
	v_fmac_f32_e32 v50, v58, v58
	v_fmac_f32_e32 v51, v56, v56
	v_add_f32_e32 v48, v48, v49
	v_add_f32_e32 v49, v50, v51
	v_add_f32_e32 v48, v48, v49
	v_add_f32_e32 v48, v66, v48
	ds_bpermute_b32 v49, v120, v48
	v_cvt_pk_bf16_f32 v50, v52, v53
	v_cvt_pk_bf16_f32 v51, v54, v55
	v_cvt_pk_bf16_f32 v52, v58, v59
	v_cvt_pk_bf16_f32 v53, v56, v57
	s_waitcnt lgkmcnt(0)
	v_add_f32_e32 v48, v48, v49
	ds_bpermute_b32 v49, v114, v48
	global_store_dwordx4 v[74:75], v[50:53], off offset:256
	s_add_u32 s98, s36, 0xb0000
	s_addc_u32 s99, s37, 0
	global_load_dwordx4 v[190:193], v168, s[98:99]
	global_load_dwordx4 v[194:197], v168, s[98:99] offset:16
	global_load_dwordx4 v[198:201], v168, s[98:99] offset:512
	global_load_dwordx4 v[202:205], v168, s[98:99] offset:528
	s_and_saveexec_b64 s[44:45], s[0:1]
	s_cbranch_execz .LBB0_905
	v_lshlrev_b64 v[50:51], 6, v[64:65]
	v_lshl_add_u64 v[50:51], s[16:17], 0, v[50:51]
	v_lshl_add_u64 v[50:51], s[38:39], 2, v[50:51]
	s_lshl_b32 s6, s54, 2
	v_lshl_add_u64 v[50:51], v[50:51], 0, s[6:7]
	s_waitcnt lgkmcnt(0)
	v_add_f32_e32 v48, v48, v49
	global_store_dword v[50:51], v48, off
.LBB0_905:
	s_or_b64 exec, exec, s[44:45]
	v_add_u32_e32 v48, 0x90, v146
	s_waitcnt lgkmcnt(0)
	v_ashrrev_i32_e32 v49, 31, v48
	v_lshlrev_b64 v[50:51], 10, v[48:49]
	v_lshl_add_u64 v[58:59], v[50:51], 0, v[144:145]
	v_lshl_add_u64 v[60:61], v[58:59], 2, s[36:37]
	v_lshl_add_u64 v[58:59], v[58:59], 1, s[40:41]
	s_waitcnt vmcnt(12)
	v_pk_add_f32 v[52:53], v[46:47], v[208:209]
	v_pk_add_f32 v[50:51], v[44:45], v[206:207]
	v_pk_add_f32 v[56:57], v[42:43], v[214:215]
	v_pk_add_f32 v[54:55], v[40:41], v[212:213]
	v_cvt_pk_bf16_f32 v40, v50, v51
	v_cvt_pk_bf16_f32 v41, v52, v53
	v_cvt_pk_bf16_f32 v42, v54, v55
	v_cvt_pk_bf16_f32 v43, v56, v57
	global_store_dwordx4 v[58:59], v[40:43], off
	s_nop 0
	v_mul_f32_e32 v51, v51, v51
	v_mul_f32_e32 v53, v53, v53
	v_mul_f32_e32 v55, v55, v55
	v_mul_f32_e32 v57, v57, v57
	v_fmac_f32_e32 v51, v50, v50
	v_fmac_f32_e32 v53, v52, v52
	v_fmac_f32_e32 v55, v54, v54
	v_fmac_f32_e32 v57, v56, v56
	v_add_f32_e32 v50, v51, v53
	v_add_f32_e32 v51, v55, v57
	v_add_f32_e32 v50, v50, v51
	v_pk_add_f32 v[38:39], v[38:39], v[218:219]
	v_pk_add_f32 v[36:37], v[36:37], v[216:217]
	v_pk_add_f32 v[40:41], v[34:35], v[222:223]
	v_pk_add_f32 v[42:43], v[32:33], v[220:221]
	v_mul_f32_e32 v32, v37, v37
	v_mul_f32_e32 v33, v39, v39
	v_mul_f32_e32 v34, v43, v43
	v_mul_f32_e32 v35, v41, v41
	v_fmac_f32_e32 v32, v36, v36
	v_fmac_f32_e32 v33, v38, v38
	v_fmac_f32_e32 v34, v42, v42
	v_fmac_f32_e32 v35, v40, v40
	v_add_f32_e32 v32, v32, v33
	v_add_f32_e32 v33, v34, v35
	v_add_f32_e32 v32, v32, v33
	v_add_f32_e32 v32, v50, v32
	ds_bpermute_b32 v33, v120, v32
	v_cvt_pk_bf16_f32 v34, v36, v37
	v_cvt_pk_bf16_f32 v35, v38, v39
	v_cvt_pk_bf16_f32 v36, v42, v43
	v_cvt_pk_bf16_f32 v37, v40, v41
	s_waitcnt lgkmcnt(0)
	v_add_f32_e32 v32, v32, v33
	ds_bpermute_b32 v33, v114, v32
	global_store_dwordx4 v[58:59], v[34:37], off offset:256
	s_and_saveexec_b64 s[44:45], s[0:1]
	s_cbranch_execz .LBB0_907
	v_lshlrev_b64 v[34:35], 6, v[48:49]
	v_lshl_add_u64 v[34:35], s[16:17], 0, v[34:35]
	v_lshl_add_u64 v[34:35], s[38:39], 2, v[34:35]
	s_lshl_b32 s6, s54, 2
	v_lshl_add_u64 v[34:35], v[34:35], 0, s[6:7]
	s_waitcnt lgkmcnt(0)
	v_add_f32_e32 v32, v32, v33
	global_store_dword v[34:35], v32, off
.LBB0_907:
	s_or_b64 exec, exec, s[44:45]
	v_add_u32_e32 v32, 0xa0, v146
	s_waitcnt lgkmcnt(0)
	v_ashrrev_i32_e32 v33, 31, v32
	v_lshlrev_b64 v[34:35], 10, v[32:33]
	v_lshl_add_u64 v[42:43], v[34:35], 0, v[144:145]
	v_lshl_add_u64 v[44:45], v[42:43], 2, s[36:37]
	v_lshl_add_u64 v[42:43], v[42:43], 1, s[40:41]
	s_waitcnt vmcnt(8)
	v_pk_add_f32 v[36:37], v[30:31], v[174:175]
	v_pk_add_f32 v[34:35], v[28:29], v[172:173]
	v_pk_add_f32 v[40:41], v[26:27], v[178:179]
	v_pk_add_f32 v[38:39], v[24:25], v[176:177]
	v_cvt_pk_bf16_f32 v24, v34, v35
	v_cvt_pk_bf16_f32 v25, v36, v37
	v_cvt_pk_bf16_f32 v26, v38, v39
	v_cvt_pk_bf16_f32 v27, v40, v41
	global_store_dwordx4 v[42:43], v[24:27], off
	s_nop 0
	v_mul_f32_e32 v35, v35, v35
	v_mul_f32_e32 v37, v37, v37
	v_mul_f32_e32 v39, v39, v39
	v_mul_f32_e32 v41, v41, v41
	v_fmac_f32_e32 v35, v34, v34
	v_fmac_f32_e32 v37, v36, v36
	v_fmac_f32_e32 v39, v38, v38
	v_fmac_f32_e32 v41, v40, v40
	v_add_f32_e32 v34, v35, v37
	v_add_f32_e32 v35, v39, v41
	v_add_f32_e32 v34, v34, v35
	v_pk_add_f32 v[22:23], v[22:23], v[184:185]
	v_pk_add_f32 v[20:21], v[20:21], v[182:183]
	v_pk_add_f32 v[24:25], v[18:19], v[188:189]
	v_pk_add_f32 v[26:27], v[16:17], v[186:187]
	v_mul_f32_e32 v16, v21, v21
	v_mul_f32_e32 v17, v23, v23
	v_mul_f32_e32 v18, v27, v27
	v_mul_f32_e32 v19, v25, v25
	v_fmac_f32_e32 v16, v20, v20
	v_fmac_f32_e32 v17, v22, v22
	v_fmac_f32_e32 v18, v26, v26
	v_fmac_f32_e32 v19, v24, v24
	v_add_f32_e32 v16, v16, v17
	v_add_f32_e32 v17, v18, v19
	v_add_f32_e32 v16, v16, v17
	v_add_f32_e32 v16, v34, v16
	ds_bpermute_b32 v17, v120, v16
	v_cvt_pk_bf16_f32 v18, v20, v21
	v_cvt_pk_bf16_f32 v19, v22, v23
	v_cvt_pk_bf16_f32 v20, v26, v27
	v_cvt_pk_bf16_f32 v21, v24, v25
	s_waitcnt lgkmcnt(0)
	v_add_f32_e32 v16, v16, v17
	ds_bpermute_b32 v17, v114, v16
	global_store_dwordx4 v[42:43], v[18:21], off offset:256
	s_and_saveexec_b64 s[44:45], s[0:1]
	s_cbranch_execz .LBB0_909
	v_lshlrev_b64 v[18:19], 6, v[32:33]
	v_lshl_add_u64 v[18:19], s[16:17], 0, v[18:19]
	v_lshl_add_u64 v[18:19], s[38:39], 2, v[18:19]
	s_lshl_b32 s6, s54, 2
	v_lshl_add_u64 v[18:19], v[18:19], 0, s[6:7]
	s_waitcnt lgkmcnt(0)
	v_add_f32_e32 v16, v16, v17
	global_store_dword v[18:19], v16, off
.LBB0_909:
	s_or_b64 exec, exec, s[44:45]
	v_add_u32_e32 v16, 0xb0, v146
	s_waitcnt lgkmcnt(0)
	v_ashrrev_i32_e32 v17, 31, v16
	v_lshlrev_b64 v[18:19], 10, v[16:17]
	v_lshl_add_u64 v[26:27], v[18:19], 0, v[144:145]
	v_lshl_add_u64 v[28:29], v[26:27], 2, s[36:37]
	v_lshl_add_u64 v[26:27], v[26:27], 1, s[40:41]
	s_waitcnt vmcnt(4)
	v_pk_add_f32 v[20:21], v[14:15], v[192:193]
	v_pk_add_f32 v[18:19], v[12:13], v[190:191]
	v_pk_add_f32 v[24:25], v[10:11], v[196:197]
	v_pk_add_f32 v[22:23], v[8:9], v[194:195]
	v_cvt_pk_bf16_f32 v8, v18, v19
	v_cvt_pk_bf16_f32 v9, v20, v21
	v_cvt_pk_bf16_f32 v10, v22, v23
	v_cvt_pk_bf16_f32 v11, v24, v25
	global_store_dwordx4 v[26:27], v[8:11], off
	s_nop 0
	v_mul_f32_e32 v19, v19, v19
	v_mul_f32_e32 v21, v21, v21
	v_mul_f32_e32 v23, v23, v23
	v_mul_f32_e32 v25, v25, v25
	v_fmac_f32_e32 v19, v18, v18
	v_fmac_f32_e32 v21, v20, v20
	v_fmac_f32_e32 v23, v22, v22
	v_fmac_f32_e32 v25, v24, v24
	v_add_f32_e32 v18, v19, v21
	v_add_f32_e32 v19, v23, v25
	v_add_f32_e32 v18, v18, v19
	v_pk_add_f32 v[6:7], v[6:7], v[200:201]
	v_pk_add_f32 v[4:5], v[4:5], v[198:199]
	v_pk_add_f32 v[8:9], v[2:3], v[204:205]
	v_pk_add_f32 v[10:11], v[0:1], v[202:203]
	v_mul_f32_e32 v0, v5, v5
	v_mul_f32_e32 v1, v7, v7
	v_mul_f32_e32 v2, v11, v11
	v_mul_f32_e32 v3, v9, v9
	v_fmac_f32_e32 v0, v4, v4
	v_fmac_f32_e32 v1, v6, v6
	v_fmac_f32_e32 v2, v10, v10
	v_fmac_f32_e32 v3, v8, v8
	v_add_f32_e32 v0, v0, v1
	v_add_f32_e32 v1, v2, v3
	v_add_f32_e32 v0, v0, v1
	v_add_f32_e32 v0, v18, v0
	ds_bpermute_b32 v1, v120, v0
	v_cvt_pk_bf16_f32 v2, v4, v5
	v_cvt_pk_bf16_f32 v3, v6, v7
	v_cvt_pk_bf16_f32 v4, v10, v11
	v_cvt_pk_bf16_f32 v5, v8, v9
	s_waitcnt lgkmcnt(0)
	v_add_f32_e32 v0, v0, v1
	ds_bpermute_b32 v1, v114, v0
	global_store_dwordx4 v[26:27], v[2:5], off offset:256
	s_and_saveexec_b64 s[44:45], s[0:1]
	s_cbranch_execz .LBB0_911
	v_lshlrev_b64 v[2:3], 6, v[16:17]
	v_lshl_add_u64 v[2:3], s[16:17], 0, v[2:3]
	v_lshl_add_u64 v[2:3], s[38:39], 2, v[2:3]
	s_lshl_b32 s6, s54, 2
	v_lshl_add_u64 v[2:3], v[2:3], 0, s[6:7]
	s_waitcnt lgkmcnt(0)
	v_add_f32_e32 v0, v0, v1
	global_store_dword v[2:3], v0, off

	.amdhsa_kernel _Z6mk_fwd4Args
		.amdhsa_group_segment_fixed_size 0
		.amdhsa_private_segment_fixed_size 0
		.amdhsa_kernarg_size 512
		.amdhsa_user_sgpr_count 2
		.amdhsa_user_sgpr_dispatch_ptr 0
		.amdhsa_user_sgpr_queue_ptr 0
		.amdhsa_user_sgpr_kernarg_segment_ptr 1
		.amdhsa_user_sgpr_dispatch_id 0
		.amdhsa_user_sgpr_kernarg_preload_length 0
		.amdhsa_user_sgpr_kernarg_preload_offset 0
		.amdhsa_user_sgpr_private_segment_size 0
		.amdhsa_uses_dynamic_stack 0
		.amdhsa_enable_private_segment 0
		.amdhsa_system_sgpr_workgroup_id_x 1
		.amdhsa_system_sgpr_workgroup_id_y 0
		.amdhsa_system_sgpr_workgroup_id_z 0
		.amdhsa_system_sgpr_workgroup_info 0
		.amdhsa_system_vgpr_workitem_id 2
		.amdhsa_next_free_vgpr 255
		.amdhsa_next_free_sgpr 100
		.amdhsa_accum_offset 256
		.amdhsa_reserve_vcc 1
		.amdhsa_float_round_mode_32 0
		.amdhsa_float_round_mode_16_64 0
		.amdhsa_float_denorm_mode_32 3
		.amdhsa_float_denorm_mode_16_64 3
		.amdhsa_dx10_clamp 1
		.amdhsa_ieee_mode 1
		.amdhsa_fp16_overflow 0
		.amdhsa_tg_split 0
		.amdhsa_exception_fp_ieee_invalid_op 0
		.amdhsa_exception_fp_denorm_src 0
		.amdhsa_exception_fp_ieee_div_zero 0
		.amdhsa_exception_fp_ieee_overflow 0
		.amdhsa_exception_fp_ieee_underflow 0
		.amdhsa_exception_fp_ieee_inexact 0
		.amdhsa_exception_int_div_zero 0
	.end_amdhsa_kernel

amdhsa.kernels:
  - .agpr_count:     0
    .args:
      - .offset:         0
        .size:           256
        .value_kind:     by_value
      - .offset:         256
        .size:           4
        .value_kind:     hidden_block_count_x
      - .offset:         260
        .size:           4
        .value_kind:     hidden_block_count_y
      - .offset:         264
        .size:           4
        .value_kind:     hidden_block_count_z
      - .offset:         268
        .size:           2
        .value_kind:     hidden_group_size_x
      - .offset:         270
        .size:           2
        .value_kind:     hidden_group_size_y
      - .offset:         272
        .size:           2
        .value_kind:     hidden_group_size_z
      - .offset:         274
        .size:           2
        .value_kind:     hidden_remainder_x
      - .offset:         276
        .size:           2
        .value_kind:     hidden_remainder_y
      - .offset:         278
        .size:           2
        .value_kind:     hidden_remainder_z
      - .offset:         296
        .size:           8
        .value_kind:     hidden_global_offset_x
      - .offset:         304
        .size:           8
        .value_kind:     hidden_global_offset_y
      - .offset:         312
        .size:           8
        .value_kind:     hidden_global_offset_z
      - .offset:         320
        .size:           2
        .value_kind:     hidden_grid_dims
      - .offset:         344
        .size:           8
        .value_kind:     hidden_multigrid_sync_arg
      - .offset:         376
        .size:           4
        .value_kind:     hidden_dynamic_lds_size
    .group_segment_fixed_size: 0
    .kernarg_segment_align: 8
    .kernarg_segment_size: 512
    .language:       OpenCL C
    .language_version:
      - 2
      - 0
    .max_flat_workgroup_size: 512
    .name:           _Z6mk_fwd4Args
    .private_segment_fixed_size: 0
    .sgpr_count:     106
    .sgpr_spill_count: 43
    .symbol:         _Z6mk_fwd4Args.kd
    .uniform_work_group_size: 1
    .uses_dynamic_stack: false
    .vgpr_count:     255
    .vgpr_spill_count: 0
    .wavefront_size: 64
